# phase-3 in-proj tiles rebalanced by CU co-residency: blocks paired with a scan block take 14 tiles, all others 11 (on v028)
# speedup vs baseline: 1.0056x; 1.0056x over previous
; __global__ void __launch_bounds__(256, 2) mega(Params p, int ph_lo, int ph_hi) {
;     ...
;         const int nb2 = gridDim.x >= 128 ? 64 : 0;
;         if ((int)blockIdx.x < nb2) phaseB2(p, blockIdx.x, smem, 0, B2_S1);
;         else phase_inproj(p, l, false, nb2, smem);
;         if (nb2 == 0) for (int u = blockIdx.x; u < 64; u += gridDim.x) phaseB2(p, u, smem, 0, B2_S1);
;       } break;
;       case 4: if (PHASE_ONLY >= 0 && PHASE_ONLY != 4) break; {
;         const int nb2 = gridDim.x >= 128 ? 64 : 0;
;         if ((int)blockIdx.x < nb2) phaseB2(p, blockIdx.x, smem, B2_S1, B2_S2);
;         else {
;           for (int t = blockIdx.x - nb2; t < 64 + 1024; t += gridDim.x - nb2) {
;             if (t < 64) cmp1_tile(p, t >> 5, (t >> 1) & 15, t & 1, smem);
;             else { const int tt = t - 64; kvup_tile(p, l, tt >> 2, tt & 3, smem); }
;           }
;           const int va = (int)blockIdx.x - nb2 - 64, nva = (int)gridDim.x - nb2 - 64;
;           if (nb2 && va >= 0 && nva > 0) phaseA1(p, va, nva, 0, A1_EARLY, smem);
;         }
;         if (nb2 == 0) for (int u = blockIdx.x; u < 64; u += gridDim.x) phaseB2(p, u, smem, B2_S1, B2_S2);
;       } break;
;       case 5: if (PHASE_ONLY >= 0 && PHASE_ONLY != 5) break; {
;         const int nb2 = gridDim.x >= 128 ? 64 : 0;
;         const int nvb = gridDim.x - nb2;
;         const int ubeg = (nb2 && (int)gridDim.x - nb2 - 64 > 0) ? A1_EARLY : 0;
;         const int usplit = nb2 ? ubeg + (4096 - ubeg - 3 * nb2) / nvb * nvb : 4096;
.LBB0_1:
	s_load_dwordx16 s[4:19], s[0:1], 0x0
	s_load_dwordx8 s[20:27], s[0:1], 0x180
	v_and_b32_e32 v230, 0x3ff, v0
	v_and_b32_e32 v0, 0x3fffffff, v0
	s_movk_i32 s97, 0x1000
	s_waitcnt lgkmcnt(0)
	v_writelane_b32 v250, s4, 2
	s_movk_i32 s33, 0x7f
	s_mov_b32 s96, 0x3e38aa3b
	v_writelane_b32 v250, s5, 3
	v_writelane_b32 v250, s6, 4
	v_writelane_b32 v250, s7, 5
	v_writelane_b32 v250, s8, 6
	v_writelane_b32 v250, s9, 7
	v_writelane_b32 v250, s10, 8
	v_writelane_b32 v250, s11, 9
	v_writelane_b32 v250, s12, 10
	v_writelane_b32 v250, s13, 11
	v_writelane_b32 v250, s14, 12
	v_writelane_b32 v250, s15, 13
	v_writelane_b32 v250, s16, 14
	v_writelane_b32 v250, s17, 15
	v_writelane_b32 v250, s18, 16
	v_writelane_b32 v250, s19, 17
	s_load_dwordx16 s[4:19], s[0:1], 0x40
	v_mov_b32_e32 v227, 0x358637bd
	v_mov_b32_e32 v232, 0x10900
	v_mov_b32_e32 v233, 0x10a00
	v_mov_b32_e32 v247, 0x10910
	s_waitcnt lgkmcnt(0)
	v_writelane_b32 v250, s4, 18
	v_mov_b32_e32 v245, 0x10920
	v_mov_b32_e32 v246, 0x10930
	v_writelane_b32 v250, s5, 19
	v_writelane_b32 v250, s6, 20
	v_writelane_b32 v250, s7, 21
	v_writelane_b32 v250, s8, 22
	v_writelane_b32 v250, s9, 23
	v_writelane_b32 v250, s10, 24
	v_writelane_b32 v250, s11, 25
	v_writelane_b32 v250, s12, 26
	v_writelane_b32 v250, s13, 27
	v_writelane_b32 v250, s14, 28
	v_writelane_b32 v250, s15, 29
	v_writelane_b32 v250, s16, 30
	v_writelane_b32 v250, s17, 31
	v_writelane_b32 v250, s18, 32
	v_writelane_b32 v250, s19, 33
	s_load_dwordx16 s[68:83], s[0:1], 0x80
	s_load_dwordx16 s[36:51], s[0:1], 0xc0
	s_load_dwordx16 s[4:19], s[0:1], 0x100
	v_mov_b32_e32 v224, 0x10940
	v_mov_b32_e32 v225, 0x10950
	v_mov_b32_e32 v248, 0x10960
	v_mov_b32_e32 v226, 0x10970
	s_waitcnt lgkmcnt(0)
	v_writelane_b32 v250, s4, 34
	v_mov_b32_e32 v228, 0x10980
	v_mov_b32_e32 v229, 0x10990
	v_writelane_b32 v250, s5, 35
	v_writelane_b32 v250, s6, 36
	v_writelane_b32 v250, s7, 37
	v_writelane_b32 v250, s8, 38
	v_writelane_b32 v250, s9, 39
	v_writelane_b32 v250, s10, 40
	v_writelane_b32 v250, s11, 41
	v_writelane_b32 v250, s12, 42
	v_writelane_b32 v250, s13, 43
	v_writelane_b32 v250, s14, 44
	v_writelane_b32 v250, s15, 45
	v_writelane_b32 v250, s16, 46
	v_writelane_b32 v250, s17, 47
	v_writelane_b32 v250, s18, 48
	v_writelane_b32 v250, s19, 49
	s_load_dwordx16 s[52:67], s[0:1], 0x140
	s_load_dwordx4 s[4:7], s[0:1], 0x1a0
	s_load_dword s18, s[0:1], 0x1b8
	s_mov_b32 s16, s2
	s_mov_b32 s15, 0
	v_mov_b32_e32 v231, 0x109a0
	s_waitcnt lgkmcnt(0)
	v_writelane_b32 v250, s4, 50
	v_mov_b32_e32 v239, 0x109b0
	v_mov_b32_e32 v240, 0x109c0
	v_writelane_b32 v250, s5, 51
	v_writelane_b32 v250, s6, 52
	v_writelane_b32 v250, s7, 53
	s_add_u32 s4, s0, 0x1b8
	s_addc_u32 s5, s1, 0
	v_writelane_b32 v250, s4, 54
	s_lshr_b32 s0, s2, 3
	s_cmpk_lt_u32 s2, 0x1000
	v_writelane_b32 v250, s5, 55
	v_writelane_b32 v250, s0, 56
	s_cselect_b64 s[0:1], -1, 0
	v_writelane_b32 v250, s0, 57
	s_lshl_b32 s94, s18, 2
	v_mov_b32_e32 v241, 0x109d0
	v_writelane_b32 v250, s1, 58
	s_lshl_b32 s0, s2, 9
	s_and_b32 s0, s0, 0xe00
	v_writelane_b32 v250, s0, 59
	s_lshr_b32 s0, s18, 3
	v_writelane_b32 v250, s0, 60
	s_lshl_b32 s0, s2, 2
	v_writelane_b32 v250, s0, 61
	s_lshr_b32 s0, s18, 1
	s_sub_i32 s0, s2, s0
	s_lshl_b32 s1, s0, 2
	s_cmp_gt_i32 s0, -1
	v_writelane_b32 v250, s1, 62
	s_cselect_b64 s[0:1], -1, 0
	v_writelane_b32 v250, s0, 63
	v_mov_b32_e32 v242, 0x109e0
	v_mov_b32_e32 v243, 0x109f0
	v_writelane_b32 v251, s1, 0
	s_lshl_b32 s0, s18, 1
	s_and_b32 s0, s0, -4
	s_cmpk_lt_u32 s2, 0x800
	v_writelane_b32 v251, s0, 1
	s_cselect_b64 s[0:1], -1, 0
	v_writelane_b32 v251, s0, 2
	v_mov_b32_e32 v234, 0x7f
	v_mov_b32_e32 v235, 0xf149f2ca
	v_writelane_b32 v251, s1, 3
	s_lshl_b32 s0, s2, 8
	s_and_b32 s0, s0, 0x700
	s_cmpk_lt_u32 s18, 0x80
	s_cselect_b64 s[4:5], -1, 0
	s_cmpk_gt_u32 s18, 0x7f
	s_cselect_b64 s[2:3], -1, 0
	v_writelane_b32 v251, s0, 4
	s_and_b64 s[0:1], s[2:3], exec
	s_cselect_b32 s19, 64, 0
	s_cselect_b32 s11, 0xffffffc0, 0
	s_sub_i32 s14, s18, s19
	s_cmp_gt_i32 s14, 64
	s_cselect_b64 s[0:1], -1, 0
	v_writelane_b32 v251, s2, 5
	s_and_b64 s[8:9], s[2:3], s[0:1]
	s_and_b64 s[0:1], s[8:9], exec
	v_writelane_b32 v251, s3, 6
	s_cselect_b32 s3, 0x300, 0
	s_abs_i32 s2, s14
	v_cvt_f32_u32_e32 v1, s2
	s_mul_i32 s10, s19, -3
	s_sub_i32 s6, 0, s2
	s_sub_i32 s0, s10, s3
	v_rcp_iflag_f32_e32 v1, v1
	s_addk_i32 s0, 0x1000
	s_ashr_i32 s1, s0, 31
	s_abs_i32 s0, s0
	v_mul_f32_e32 v1, 0x4f7ffffe, v1
	v_cvt_u32_f32_e32 v1, v1
	v_mov_b32_e32 v236, 0x4e6e6b28
	v_mov_b32_e32 v237, 0x10800
	v_mov_b32_e32 v238, 0xd00
	v_readfirstlane_b32 s7, v1
	s_mul_i32 s6, s6, s7
	s_mul_hi_u32 s6, s7, s6
	s_add_i32 s7, s7, s6
	s_mul_hi_u32 s6, s0, s7
	s_mul_i32 s6, s6, s2
	s_sub_i32 s0, s0, s6
	s_sub_i32 s6, s0, s2
	s_cmp_ge_u32 s0, s2
	s_cselect_b32 s0, s6, s0
	s_sub_i32 s6, s0, s2
	s_cmp_ge_u32 s0, s2
	s_cselect_b32 s0, s6, s0
	s_xor_b32 s0, s0, s1
	s_sub_i32 s0, s1, s0
	s_add_i32 s10, s10, s0
	s_addk_i32 s10, 0xffe0
	s_cmp_ge_i32 s16, s19
	s_cselect_b64 s[0:1], -1, 0
	s_sub_i32 s28, s16, s19
	v_writelane_b32 v251, s0, 7
	s_add_i32 s2, s28, 32
	s_cmp_ge_i32 s2, s14
	v_mov_b32_e32 v1, 0
	v_writelane_b32 v251, s1, 8
	s_cselect_b64 s[0:1], -1, 0
	v_writelane_b32 v251, s0, 9
	s_ashr_i32 s17, s16, 31
	s_ashr_i32 s2, s16, 2
	v_writelane_b32 v251, s1, 10
	s_add_i32 s0, s3, s28
	v_writelane_b32 v251, s0, 11
	s_and_b32 s29, s16, 3
	s_lshl_b64 s[0:1], s[16:17], 16
	s_add_u32 s0, s60, s0
	s_addc_u32 s1, s61, s1
	v_writelane_b32 v251, s0, 12
	v_mov_b32_e32 v244, 0x10804
	s_nop 0
	v_writelane_b32 v251, s1, 13
	s_lshl_b32 s0, s2, 5
	v_writelane_b32 v251, s0, 14
	s_lshl_b32 s0, s2, 7
	s_or_b32 s0, s0, s29
	s_or_b32 s6, s0, 0x60
	s_ashr_i32 s7, s6, 31
; DI void phase_inproj(const Params& p, int l, bool partB, int skipb, char* smem) {
;   const int ntn = partB ? 13 : 20;
;   const int ntiles = 256 * ntn;
;   const int per = ntiles >> 3;
;   const int vblk = blockIdx.x - skipb, nvb = gridDim.x - skipb;
;   for (int idx = vblk >> 3; idx < per; idx += nvb >> 3) {
;     const int t = (vblk & 7) * per + idx;
	s_lshl_b64 s[12:13], s[6:7], 13
	s_lshl_b64 s[6:7], s[6:7], 14
	s_add_u32 s30, s62, s6
	s_addc_u32 s31, s63, s7
	v_writelane_b32 v251, s30, 15
	s_nop 1
	v_writelane_b32 v251, s31, 16
	s_add_u32 s30, s64, s6
	s_addc_u32 s31, s65, s7
	v_writelane_b32 v251, s30, 17
	s_nop 1
	v_writelane_b32 v251, s31, 18
	s_add_u32 s30, s66, s6
	s_addc_u32 s31, s67, s7
	v_writelane_b32 v251, s30, 19
	s_add_u32 s12, s20, s12
	s_addc_u32 s13, s21, s13
	v_writelane_b32 v251, s31, 20
	v_writelane_b32 v251, s12, 21
	s_add_u32 s6, s22, s6
	s_addc_u32 s7, s23, s7
	v_writelane_b32 v251, s13, 22
	s_lshl_b32 s2, s2, 11
	v_writelane_b32 v251, s6, 23
	s_cmp_lt_i32 s16, 64
	s_nop 0
	v_writelane_b32 v251, s7, 24
	s_cselect_b64 s[6:7], -1, 0
	s_cmpk_lt_i32 s28, 0x440
	s_cselect_b64 s[12:13], -1, 0
	v_writelane_b32 v251, s12, 25
	s_cmp_lg_u64 s[40:41], 0
	s_nop 0
	v_writelane_b32 v251, s13, 26
	s_cselect_b64 s[12:13], -1, 0
	s_add_i32 s1, s11, s18
	v_writelane_b32 v251, s12, 27
	s_cmp_gt_i32 s28, 63
	s_nop 0
	v_writelane_b32 v251, s13, 28
	s_cselect_b64 s[12:13], -1, 0
	v_writelane_b32 v251, s1, 29
	s_and_b64 s[8:9], s[8:9], s[12:13]
	v_writelane_b32 v251, s8, 30
	s_sub_i32 s1, s14, 64
	s_nop 0
	v_writelane_b32 v251, s9, 31
	v_writelane_b32 v251, s1, 32
	s_sub_i32 s1, s28, 64
	s_cmpk_lt_u32 s1, 0x300
	v_writelane_b32 v251, s1, 33
	s_cselect_b64 s[8:9], -1, 0
	v_writelane_b32 v251, s8, 34
	s_nop 1
	v_writelane_b32 v251, s9, 35
	s_or_b32 s8, s0, 0x4c
	s_ashr_i32 s9, s8, 31
	s_lshl_b64 s[12:13], s[8:9], 13
	s_lshl_b64 s[8:9], s[8:9], 14
	s_add_u32 s30, s62, s8
	s_addc_u32 s31, s63, s9
	v_writelane_b32 v251, s30, 36
	s_nop 1
	v_writelane_b32 v251, s31, 37
	s_add_u32 s30, s64, s8
	s_addc_u32 s31, s65, s9
	v_writelane_b32 v251, s30, 38
	s_nop 1
	v_writelane_b32 v251, s31, 39
	s_add_u32 s30, s66, s8
	s_addc_u32 s31, s67, s9
	v_writelane_b32 v251, s30, 40
	s_add_u32 s12, s20, s12
	s_addc_u32 s13, s21, s13
	v_writelane_b32 v251, s31, 41
	v_writelane_b32 v251, s12, 42
	s_add_u32 s8, s22, s8
	s_addc_u32 s9, s23, s9
	v_writelane_b32 v251, s13, 43
	v_writelane_b32 v251, s8, 44
	s_cmpk_lt_u32 s28, 0x1400
	s_nop 0
	v_writelane_b32 v251, s9, 45
	s_cselect_b64 s[8:9], -1, 0
	v_writelane_b32 v251, s8, 46
	s_lshr_b32 s1, s28, 3
	s_and_b32 s11, s16, 7
	v_writelane_b32 v251, s9, 47
	v_writelane_b32 v251, s28, 48
	s_add_i32 s8, s1, -24
	s_cmp_lt_u32 s1, 24
	s_cselect_b32 s12, 8, 0
	s_add_i32 s12, s12, s1
	s_addk_i32 s12, 104
	s_cmp_lt_u32 s8, 8
	s_cselect_b32 s9, 8, 48
	s_cselect_b32 s1, s8, s12
	s_nop 0
	v_writelane_b32 v251, s1, 49
	s_mul_i32 s1, s11, 0x280
	v_writelane_b32 v251, s1, 50
	v_writelane_b32 v251, s14, 51
	v_writelane_b32 v251, s9, 52
	s_ashr_i32 s1, s0, 31
	s_lshl_b64 s[8:9], s[0:1], 13
	s_lshl_b64 s[12:13], s[0:1], 14
	s_add_u32 s30, s62, s12
	s_addc_u32 s31, s63, s13
	v_writelane_b32 v251, s30, 53
	s_nop 1
	v_writelane_b32 v251, s31, 54
	s_add_u32 s30, s64, s12
	s_addc_u32 s31, s65, s13
	v_writelane_b32 v251, s30, 55
	s_nop 1
	v_writelane_b32 v251, s31, 56
	s_add_u32 s30, s66, s12
	s_addc_u32 s31, s67, s13
	v_writelane_b32 v251, s30, 57
	s_add_u32 s8, s20, s8
	s_addc_u32 s9, s21, s9
	v_writelane_b32 v251, s31, 58
	v_writelane_b32 v251, s8, 59
	s_nop 1
	v_writelane_b32 v251, s9, 60
	s_add_u32 s8, s22, s12
	s_addc_u32 s9, s23, s13
	v_writelane_b32 v251, s8, 61
	s_cmpk_lt_i32 s16, 0x800
	s_nop 0
	v_writelane_b32 v251, s9, 62
	s_cselect_b64 s[8:9], -1, 0
	s_ashr_i32 s1, s16, 3
	v_writelane_b32 v251, s8, 63
	s_cmpk_lt_i32 s1, 0x1a0
	s_nop 0
	v_writelane_b32 v252, s9, 0
	v_writelane_b32 v252, s1, 1
	s_cselect_b64 s[8:9], -1, 0
	v_writelane_b32 v252, s8, 2
	s_mul_i32 s1, s11, 0x1a0
	s_add_i32 s11, s16, 0xe0
	v_writelane_b32 v252, s9, 3
	v_writelane_b32 v252, s1, 4
	s_ashr_i32 s1, s18, 3
	v_writelane_b32 v252, s1, 5
	s_add_i32 s1, s18, -1
	v_writelane_b32 v252, s1, 6
	s_add_i32 s1, s16, 64
	s_add_i32 s8, s16, 0x60
	s_add_i32 s9, s16, 0x50
	s_add_u32 s12, s80, 0x100000
	s_addc_u32 s13, s81, 0
	v_writelane_b32 v252, s12, 7
	s_nop 1
	v_writelane_b32 v252, s13, 8
	s_add_i32 s12, s16, 0x58
	s_add_u32 s30, s82, 0x10000
	v_writelane_b32 v252, s68, 9
	s_addc_u32 s31, s83, 0
	s_and_b64 s[4:5], s[4:5], s[6:7]
	v_writelane_b32 v252, s69, 10
	v_writelane_b32 v252, s70, 11
	v_writelane_b32 v252, s71, 12
	v_writelane_b32 v252, s72, 13
	v_writelane_b32 v252, s73, 14
	v_writelane_b32 v252, s74, 15
	v_writelane_b32 v252, s75, 16
	v_writelane_b32 v252, s76, 17
	v_writelane_b32 v252, s77, 18
	v_writelane_b32 v252, s78, 19
	v_writelane_b32 v252, s79, 20
	v_writelane_b32 v252, s80, 21
	v_writelane_b32 v252, s81, 22
	v_writelane_b32 v252, s82, 23
	v_writelane_b32 v252, s83, 24
	v_writelane_b32 v252, s30, 25
	s_add_i32 s13, s16, 0x160
	s_add_i32 s14, s16, 0xc8
	v_writelane_b32 v252, s31, 26
	v_cmp_eq_u32_e64 s[30:31], 0, v0
	v_cvt_f32_u32_e32 v0, s18
	s_movk_i32 s76, 0x90
	v_writelane_b32 v252, s30, 27
	s_movk_i32 s77, 0x200
	v_rcp_iflag_f32_e32 v0, v0
	v_writelane_b32 v252, s31, 28
	v_writelane_b32 v252, s4, 29
	s_movk_i32 s79, 0x210
	v_mul_f32_e32 v0, 0x4f7ffffe, v0
	v_cvt_u32_f32_e32 v0, v0
	v_writelane_b32 v252, s5, 30
	s_add_i32 s4, s10, 0x1000
	v_writelane_b32 v252, s4, 31
	s_sub_i32 s4, 0, s18
	v_readfirstlane_b32 s5, v0
	s_mul_i32 s4, s4, s5
	s_mul_hi_u32 s4, s5, s4
	s_add_i32 s5, s5, s4
	s_mul_hi_u32 s4, s16, s5
	s_mul_i32 s4, s4, s18
	s_sub_i32 s4, s16, s4
	s_sub_i32 s6, s4, s18
	s_cmp_ge_u32 s4, s18
	s_cselect_b32 s4, s6, s4
	s_sub_i32 s6, s4, s18
	s_cmp_ge_u32 s4, s18
	s_cselect_b32 s4, s6, s4
	v_writelane_b32 v252, s4, 32
	s_cmpk_lt_i32 s4, 0x720
	s_mul_hi_u32 s4, s1, s5
	s_mul_i32 s4, s4, s18
	s_cselect_b64 s[6:7], -1, 0
	s_sub_i32 s1, s1, s4
	s_sub_i32 s4, s1, s18
	s_cmp_ge_u32 s1, s18
; #define TIDX (tid_launder())
; DI void tr_job(const float* __restrict__ src, int ld, int K, int Nsrc, bool map, bf16_t* __restrict__ dst, int Nrows,
;                float* lds, int rot) {
;   const int ntk = K / 64, ntiles = (Nrows / 64) * ntk;
;   const int vb = (blockIdx.x + rot) % gridDim.x;
;   const int tx = TIDX & 63, ty = TIDX >> 6;
;   for (int t = vb; t < ntiles; t += gridDim.x) {
; DI void phase0(const Params& p, int l, char* smem) {
;   float* lds = (float*)smem;
;   if (l == 0 && blockIdx.x == gridDim.x - 1) build_lut(p, p.lutg);
;   tr_job(p.w_in + (size_t)l * 1024 * 7260, 7260, 1024, 7260, true, p.wt_in, 7296, lds, 0);
;   tr_job(p.a_w_ukv + (size_t)l * 128 * 512, 512, 128, 512, false, p.wt_ukv, 512, lds, 64);
;   for (int kv = 0; kv < 2; ++kv) {
;     tr_job(p.c_phi_w1 + ((size_t)l * 2 + kv) * 2048 * 256, 256, 2048, 256, false, p.wt_phi1 + (size_t)kv * 256 * 2048, 256, lds, 96 + kv * 128);
;     tr_job(p.c_phi_w2 + ((size_t)l * 2 + kv) * 256 * 64, 64, 256, 64, false, p.wt_phi2 + (size_t)kv * 128 * 256, 128, lds, 80 + kv * 8);
;   }
;   tr_job(p.w_branch + (size_t)l * 1024 * 1024, 1024, 1024, 1024, false, p.wt_br, 1024, lds, 352);
;   tr_job(p.w_out + (size_t)l * 1024 * 1024, 1024, 1024, 1024, false, p.wt_out, 1024, lds, 96);
;   {
;     const int vb = (blockIdx.x + 200) % gridDim.x;
;     for (int j = vb; j < 16; j += gridDim.x) {
	s_cselect_b32 s1, s4, s1
	s_sub_i32 s4, s1, s18
	v_writelane_b32 v252, s6, 33
	s_cmp_ge_u32 s1, s18
	s_cselect_b32 s1, s4, s1
	v_writelane_b32 v252, s7, 34
	v_writelane_b32 v252, s1, 35
	s_cmp_lt_i32 s1, 16
	s_mul_hi_u32 s1, s8, s5
	s_mul_i32 s1, s1, s18
	s_cselect_b64 s[6:7], -1, 0
	s_sub_i32 s1, s8, s1
	s_sub_i32 s4, s1, s18
	s_cmp_ge_u32 s1, s18
	s_cselect_b32 s1, s4, s1
	s_sub_i32 s4, s1, s18
	v_writelane_b32 v252, s6, 36
	s_cmp_ge_u32 s1, s18
	v_mbcnt_lo_u32_b32 v0, -1, 0
	v_writelane_b32 v252, s7, 37
	s_cselect_b32 s6, s4, s1
	s_mul_hi_u32 s1, s9, s5
	s_cmpk_lt_i32 s6, 0x80
	s_mul_i32 s1, s1, s18
	s_cselect_b64 s[30:31], -1, 0
	s_sub_i32 s1, s9, s1
	s_sub_i32 s4, s1, s18
	s_cmp_ge_u32 s1, s18
	s_cselect_b32 s1, s4, s1
	s_sub_i32 s4, s1, s18
	v_writelane_b32 v252, s30, 38
	s_cmp_ge_u32 s1, s18
	s_cselect_b32 s1, s4, s1
	v_writelane_b32 v252, s31, 39
	v_writelane_b32 v252, s1, 40
	s_cmp_lt_i32 s1, 8
	s_mul_hi_u32 s1, s11, s5
	s_mul_i32 s1, s1, s18
	s_cselect_b64 s[8:9], -1, 0
	s_sub_i32 s1, s11, s1
	s_sub_i32 s4, s1, s18
	s_cmp_ge_u32 s1, s18
	s_cselect_b32 s1, s4, s1
	s_sub_i32 s4, s1, s18
	v_writelane_b32 v252, s8, 41
	s_cmp_ge_u32 s1, s18
	s_cselect_b32 s1, s4, s1
	v_writelane_b32 v252, s9, 42
	v_writelane_b32 v252, s1, 43
	s_cmpk_lt_i32 s1, 0x80
	s_mul_hi_u32 s1, s12, s5
	s_mul_i32 s1, s1, s18
	s_cselect_b64 s[8:9], -1, 0
	s_sub_i32 s1, s12, s1
	s_sub_i32 s4, s1, s18
	s_cmp_ge_u32 s1, s18
	s_cselect_b32 s1, s4, s1
	s_sub_i32 s4, s1, s18
	v_writelane_b32 v252, s8, 44
	s_cmp_ge_u32 s1, s18
	s_cselect_b32 s1, s4, s1
	v_writelane_b32 v252, s9, 45
	v_writelane_b32 v252, s1, 46
	s_cmp_lt_i32 s1, 8
	s_mul_hi_u32 s1, s13, s5
	s_mul_i32 s1, s1, s18
	s_cselect_b64 s[8:9], -1, 0
	s_sub_i32 s1, s13, s1
	s_sub_i32 s4, s1, s18
	s_cmp_ge_u32 s1, s18
	s_cselect_b32 s1, s4, s1
	s_sub_i32 s4, s1, s18
	s_cmp_ge_u32 s1, s18
	v_writelane_b32 v252, s8, 47
	s_cselect_b32 s1, s4, s1
	s_cmpk_lt_i32 s1, 0x100
	v_writelane_b32 v252, s9, 48
	v_writelane_b32 v252, s1, 49
	s_cselect_b64 s[8:9], -1, 0
	v_writelane_b32 v252, s8, 50
	s_mul_hi_u32 s1, s14, s5
	s_cmpk_lt_i32 s6, 0x100
	v_writelane_b32 v252, s9, 51
	s_mul_i32 s1, s1, s18
	v_writelane_b32 v252, s6, 52
	s_cselect_b64 s[6:7], -1, 0
	s_sub_i32 s1, s14, s1
	s_sub_i32 s4, s1, s18
	s_cmp_ge_u32 s1, s18
	s_cselect_b32 s1, s4, s1
	s_sub_i32 s4, s1, s18
	s_cmp_ge_u32 s1, s18
	s_cselect_b32 s4, s4, s1
	v_writelane_b32 v252, s6, 53
	s_cmp_lt_i32 s4, 16
	s_mov_b32 s82, 0xf149f2ca
	v_writelane_b32 v252, s7, 54
	s_cselect_b64 s[6:7], -1, 0
	v_writelane_b32 v252, s6, 55
	s_movk_i32 s80, 0x2000
	s_movk_i32 s81, 0x3000
	v_writelane_b32 v252, s7, 56
	s_add_u32 s6, s48, 0x200
	v_writelane_b32 v252, s36, 57
	s_addc_u32 s7, s49, 0
	s_ashr_i32 s95, s94, 31
	v_writelane_b32 v253, s43, 0
	v_writelane_b32 v253, s44, 1
	v_writelane_b32 v253, s45, 2
	v_writelane_b32 v253, s46, 3
	v_writelane_b32 v253, s47, 4
	v_writelane_b32 v253, s48, 5
	v_writelane_b32 v253, s49, 6
	v_writelane_b32 v253, s50, 7
	v_writelane_b32 v253, s51, 8
	v_writelane_b32 v253, s6, 9
	s_lshl_b64 s[44:45], s[94:95], 11
	v_writelane_b32 v252, s37, 58
	v_writelane_b32 v253, s7, 10
	s_add_u32 s6, s54, 0xc00
	v_writelane_b32 v253, s52, 11
	s_addc_u32 s7, s55, 0
	s_sub_i32 s1, s19, s3
	v_writelane_b32 v253, s53, 12
	v_writelane_b32 v253, s54, 13
	v_writelane_b32 v253, s55, 14
	v_writelane_b32 v253, s56, 15
	v_writelane_b32 v253, s57, 16
	v_writelane_b32 v253, s58, 17
	v_writelane_b32 v253, s59, 18
	v_writelane_b32 v253, s60, 19
	v_writelane_b32 v253, s61, 20
	v_writelane_b32 v253, s62, 21
	v_writelane_b32 v253, s63, 22
	v_writelane_b32 v253, s64, 23
	v_writelane_b32 v253, s65, 24
	v_writelane_b32 v253, s66, 25
	v_writelane_b32 v253, s67, 26
	v_writelane_b32 v253, s6, 27
	s_sub_i32 s1, s1, s16
	s_addk_i32 s1, 0xfff
	v_writelane_b32 v253, s7, 28
	s_ashr_i32 s3, s2, 31
	v_writelane_b32 v253, s1, 29
	s_lshl_b64 s[2:3], s[2:3], 10
	s_lshl_b32 s1, s29, 8
	s_sub_i32 s5, s19, s18
	s_or_b32 s1, s2, s1
	s_add_u32 s2, s26, s1
	s_addc_u32 s3, s27, s3
	s_add_u32 s6, s2, 0x180000
	v_writelane_b32 v253, s2, 30
	s_addc_u32 s7, s3, 0
	v_readlane_b32 s52, v250, 18
	v_writelane_b32 v253, s3, 31
	v_writelane_b32 v253, s6, 32
	s_add_u32 s2, s26, 0x180000
	v_readlane_b32 s64, v250, 30
	v_writelane_b32 v253, s7, 33
	v_writelane_b32 v253, s20, 34
	s_addc_u32 s3, s27, 0
	s_sub_i32 s1, s19, s16
	v_writelane_b32 v253, s21, 35
	v_writelane_b32 v253, s22, 36
	v_writelane_b32 v253, s23, 37
	v_writelane_b32 v253, s24, 38
	v_writelane_b32 v253, s25, 39
	v_writelane_b32 v253, s26, 40
	v_writelane_b32 v253, s27, 41
	v_writelane_b32 v253, s2, 42
	s_addk_i32 s1, 0x103f
	v_readlane_b32 s65, v250, 31
	v_writelane_b32 v253, s3, 43
	s_mov_b32 s2, s16
	v_writelane_b32 v253, s2, 44
	v_readlane_b32 s62, v250, 28
	v_readlane_b32 s63, v250, 29
	v_writelane_b32 v253, s3, 45
	v_writelane_b32 v253, s19, 46
	v_writelane_b32 v253, s1, 47
	v_writelane_b32 v253, s5, 48
	s_add_i32 s1, s5, 64
	v_writelane_b32 v253, s1, 49
	s_or_b32 s1, s0, 0x50
	v_writelane_b32 v253, s1, 50
	s_or_b32 s0, s0, 4
	v_writelane_b32 v253, s0, 51
	s_add_u32 s0, s64, 0x7c00
	v_writelane_b32 v253, s0, 52
	s_addc_u32 s0, s65, 0
	v_writelane_b32 v253, s0, 53
	v_writelane_b32 v253, s4, 54
	s_lshl_b32 s0, s4, 5
	v_writelane_b32 v253, s0, 55
	v_writelane_b32 v253, s18, 56
	s_lshl_b32 s0, s18, 5
	v_writelane_b32 v253, s0, 57
	s_add_u32 s0, s62, 0x7c
	v_writelane_b32 v252, s38, 59
	v_writelane_b32 v253, s0, 58
	s_addc_u32 s0, s63, 0
	v_writelane_b32 v252, s39, 60
	v_writelane_b32 v253, s0, 59
	v_writelane_b32 v252, s40, 61
	v_writelane_b32 v253, s29, 60
	v_writelane_b32 v252, s41, 62
	v_writelane_b32 v253, s44, 61
	v_writelane_b32 v252, s42, 63
	s_movk_i32 s42, 0x100
	s_mov_b64 s[40:41], 0x10000
	s_movk_i32 s37, 0x80
	s_movk_i32 s43, 0xfff
	s_movk_i32 s46, 0x7fff
	s_mov_b32 s47, 0xfffffc0
	s_mov_b64 s[48:49], 0x8000
	s_movk_i32 s50, 0xd00
	s_mov_b32 s51, 0x8000
	s_movk_i32 s83, 0x1eff
	s_movk_i32 s95, 0x4000
	v_mbcnt_hi_u32_b32 v249, -1, v0
	v_writelane_b32 v253, s45, 62
	v_readlane_b32 s53, v250, 19
	v_readlane_b32 s54, v250, 20
	v_readlane_b32 s55, v250, 21
	v_readlane_b32 s56, v250, 22
	v_readlane_b32 s57, v250, 23
	v_readlane_b32 s58, v250, 24
	v_readlane_b32 s59, v250, 25
	v_readlane_b32 s60, v250, 26
	v_readlane_b32 s61, v250, 27
	v_readlane_b32 s66, v250, 32
	v_readlane_b32 s67, v250, 33
	s_branch .LBB0_5

; DI void phase_inproj(const Params& p, int l, bool partB, int skipb, char* smem) {
;     ...
;   for (int idx = vblk >> 3; idx < per; idx += nvb >> 3) {
;     const int t = (vblk & 7) * per + idx;
;     const int mt = t / ntn; int tn = t % ntn;
;     if (partB) tn += 12; else if (tn >= 12) tn += 13;
;     inproj_tile(p, l, mt, tn, smem);
.LBB0_1954:
	v_readlane_b32 s0, v251, 52
	s_add_i32 s10, s10, s0
	s_cmp_eq_u32 s0, 8
	s_movk_i32 s0, 0x280
	s_cselect_b32 s0, 112, s0
	s_cmp_lt_i32 s10, s0
	s_waitcnt vmcnt(63) expcnt(7) lgkmcnt(15)
	s_barrier
	s_cbranch_scc0 .LBB0_1767
